# shared context chain without its first workgroup barrier (the phase starts behind the grid barrier, the LDS is idle)
# baseline (speedup 1.0000x reference)
.Lsgu_pre_skip:
	s_add_u32 s35, s63, 0x80
	v_and_b32_e32 v16, 63, v206
	v_lshrrev_b32_e32 v17, 6, v206
	v_and_b32_e32 v0, 15, v16
	v_readfirstlane_b32 s40, v17
	v_lshrrev_b32_e32 v1, 4, v16
	s_sub_u32 s38, s35, 0x80
	s_and_b32 s42, s40, 3
	s_lshr_b32 s43, s40, 2
	s_lshl_b32 s43, s43, 2
	s_lshr_b32 s100, s38, 4
	s_lshl_b32 s101, s100, 1
	s_bfe_u32 s41, s38, 0x30001
	s_and_b32 s39, s38, 1
	s_lshl_b32 s52, s100, 1
	s_add_u32 s52, s52, s36
	s_lshl_b32 s52, s52, 1
	s_add_u32 s52, s52, s39
	s_lshl_b32 s52, s52, 3
	s_add_u32 s52, s52, s41
	s_add_u32 s100, s101, 1
	s_cmp_eq_u32 s39, 0
	s_cselect_b32 s101, s101, s100
	s_cselect_b32 s92, 0, -1
	s_mov_b32 s98, 0xfffe0000
	s_cselect_b32 s98, 0x20000, s98
	s_mov_b32 s99, 0xffff0000
	s_cselect_b32 s99, 0x10000, s99
	s_mov_b32 s50, 0xfffc0000
	s_cselect_b32 s50, 0x40000, s50
	s_mov_b32 s51, 0xffffe000
	s_cselect_b32 s51, 0x2000, s51
	s_lshl_b32 s100, s101, 3
	s_add_u32 s100, s100, s41
	s_lshl_b32 s100, s100, 14
	s_lshl_b32 s53, s40, 10
	s_add_u32 s100, s100, s53
	s_add_u32 s100, s100, 0xc184000
	s_add_u32 s44, s96, s100
	s_addc_u32 s45, s97, 0
	s_lshl_b32 s100, s101, 1
	s_lshr_b32 s54, s41, 2
	s_add_u32 s100, s100, s54
	s_lshl_b32 s100, s100, 15
	s_add_u32 s100, s100, s53
	s_add_u32 s100, s100, 0xbe84000
	s_add_u32 s46, s96, s100
	s_addc_u32 s47, s97, 0
	s_lshl_b32 s100, s101, 1
	s_add_u32 s100, s100, s39
	s_lshl_b32 s100, s100, 3
	s_add_u32 s100, s100, s41
	s_lshl_b32 s54, s100, 14
	s_lshl_b32 s55, s42, 12
	s_add_u32 s54, s54, s55
	s_lshl_b32 s55, s43, 5
	s_add_u32 s54, s54, s55
	s_add_u32 s54, s54, 0xac84000
	s_add_u32 s48, s96, s54
	s_addc_u32 s49, s97, 0
	s_lshl_b32 s100, s100, 9
	s_add_u32 s54, s100, 0xcae4000
	s_add_u32 s58, s96, s54
	s_addc_u32 s59, s97, 0
	s_cmp_eq_u32 s39, 0
	s_cselect_b32 s54, 0x1fc, 0
	s_add_u32 s58, s58, s54
	s_addc_u32 s59, s59, 0
	global_load_dword v22, v2, s[58:59]
	s_add_u32 s58, s58, s51
	s_addc_u32 s59, s59, s92
	global_load_dword v23, v2, s[58:59]
	s_add_u32 s54, s100, 0xcb44000
	s_add_u32 s58, s96, s54
	s_addc_u32 s59, s97, 0
	s_cmp_eq_u32 s39, 0
	s_cbranch_scc1 .Lcs_fw
	s_sub_u32 s58, s58, 0x2000
	s_subb_u32 s59, s59, 0
